# v18: v16 + GEMM accumulator re-init with v_mov_b64 (64 instead of 127 movs per tile, 6 GEMM instances)
# baseline (speedup 1.0000x reference)
; template <class Epi, bool ALIGN_EPI = true>
; __device__ __forceinline__ void gemm_phase(LAS unsigned char* lds, const Gemm g, const StaticOrder& S, const Epi& E) {
;     ...
;         const bool has_next = S.next(ui + 1, nxt);
;         const char* nA = has_next ? (const char*)g.A + (size_t)nxt.pm * tstepA + (size_t)nxt.pn * g.a_pn_off * 2 : cA; const char* nB = has_next ? (const char*)g.Bt + (size_t)nxt.pn * tstepB : cB;
;     ...
;         for (int a = 0; a < 2; ++a)
; #pragma unroll
;             for (int b = 0; b < 2; ++b)
; #pragma unroll
;                 for (int m = 0; m < 4; ++m)
; #pragma unroll
;                     for (int n = 0; n < 2; ++n) acc[a][b][m][n] = (f32x4){0.f, 0.f, 0.f, 0.f};
.LBB0_58:
	s_ashr_i32 s17, s16, 31
	s_lshl_b64 s[18:19], s[16:17], 20
	s_add_u32 s18, s92, s18
	s_addc_u32 s19, s93, s19
	s_and_b64 s[20:21], s[4:5], exec
	s_cselect_b32 s17, s19, s25
	s_cselect_b32 s56, s18, s24
	s_ashr_i32 s15, s14, 31
	s_lshl_b64 s[20:21], s[14:15], 20
	s_add_u32 s20, s2, s20
	s_addc_u32 s21, s3, s21
	s_and_b64 s[28:29], s[4:5], exec
	s_cselect_b32 s15, s21, s27
	s_cselect_b32 s57, s20, s26
	s_add_u32 s58, s56, 0x80
	s_addc_u32 s59, s17, 0
	s_add_u32 s60, s26, 0x100
	v_mov_b32_e32 v0, 0
	s_addc_u32 s61, s27, 0
	s_mov_b32 s62, -2
	s_mov_b64 s[26:27], 0
	v_mov_b64 v[0:1], 0
	v_mov_b64 v[2:3], 0
	v_mov_b64 v[4:5], 0
	v_mov_b64 v[6:7], 0
	v_mov_b64 v[12:13], 0
	v_mov_b64 v[14:15], 0
	v_mov_b64 v[20:21], 0
	v_mov_b64 v[22:23], 0
	v_mov_b64 v[28:29], 0
	v_mov_b64 v[30:31], 0
	v_mov_b64 v[36:37], 0
	v_mov_b64 v[38:39], 0
	v_mov_b64 v[44:45], 0
	v_mov_b64 v[46:47], 0
	v_mov_b64 v[52:53], 0
	v_mov_b64 v[54:55], 0
	v_mov_b64 v[8:9], 0
	v_mov_b64 v[10:11], 0
	v_mov_b64 v[16:17], 0
	v_mov_b64 v[18:19], 0
	v_mov_b64 v[24:25], 0
	v_mov_b64 v[26:27], 0
	v_mov_b64 v[32:33], 0
	v_mov_b64 v[34:35], 0
	v_mov_b64 v[40:41], 0
	v_mov_b64 v[42:43], 0
	v_mov_b64 v[48:49], 0
	v_mov_b64 v[50:51], 0
	v_mov_b64 v[56:57], 0
	v_mov_b64 v[58:59], 0
	v_mov_b64 v[60:61], 0
	v_mov_b64 v[62:63], 0
	v_mov_b64 v[64:65], 0
	v_mov_b64 v[66:67], 0
	v_mov_b64 v[68:69], 0
	v_mov_b64 v[70:71], 0
	v_mov_b64 v[76:77], 0
	v_mov_b64 v[78:79], 0
	v_mov_b64 v[84:85], 0
	v_mov_b64 v[86:87], 0
	v_mov_b64 v[92:93], 0
	v_mov_b64 v[94:95], 0
	v_mov_b64 v[100:101], 0
	v_mov_b64 v[102:103], 0
	v_mov_b64 v[108:109], 0
	v_mov_b64 v[110:111], 0
	v_mov_b64 v[116:117], 0
	v_mov_b64 v[118:119], 0
	v_mov_b64 v[72:73], 0
	v_mov_b64 v[74:75], 0
	v_mov_b64 v[80:81], 0
	v_mov_b64 v[82:83], 0
	v_mov_b64 v[88:89], 0
	v_mov_b64 v[90:91], 0
	v_mov_b64 v[96:97], 0
	v_mov_b64 v[98:99], 0
	v_mov_b64 v[104:105], 0
	v_mov_b64 v[106:107], 0
	v_mov_b64 v[112:113], 0
	v_mov_b64 v[114:115], 0
	v_mov_b64 v[120:121], 0
	v_mov_b64 v[122:123], 0
	v_mov_b64 v[124:125], 0
	v_mov_b64 v[126:127], 0
	v_lshl_add_u64 v[142:143], s[24:25], 0, v[134:135]
	v_lshl_add_u64 v[144:145], s[24:25], 0, v[136:137]

; template <class Epi, bool ALIGN_EPI = true>
; __device__ __forceinline__ void gemm_phase(LAS unsigned char* lds, const Gemm g, const StaticOrder& S, const Epi& E) {
;     ...
;         const bool has_next = S.next(ui + 1, nxt);
;         const char* nA = has_next ? (const char*)g.A + (size_t)nxt.pm * tstepA + (size_t)nxt.pn * g.a_pn_off * 2 : cA; const char* nB = has_next ? (const char*)g.Bt + (size_t)nxt.pn * tstepB : cB;
;     ...
;         for (int a = 0; a < 2; ++a)
; #pragma unroll
;             for (int b = 0; b < 2; ++b)
; #pragma unroll
;                 for (int m = 0; m < 4; ++m)
; #pragma unroll
;                     for (int n = 0; n < 2; ++n) acc[a][b][m][n] = (f32x4){0.f, 0.f, 0.f, 0.f};
.LBB0_74:
	s_ashr_i32 s19, s18, 31
	s_lshl_b64 s[0:1], s[18:19], 20
	s_add_u32 s20, s92, s0
	s_addc_u32 s21, s93, s1
	s_and_b64 s[0:1], s[4:5], exec
	s_cselect_b32 s0, s21, s27
	s_cselect_b32 s1, s20, s26
	s_ashr_i32 s17, s16, 31
	s_lshl_b64 s[22:23], s[16:17], 20
	s_add_u32 s22, s33, s22
	s_addc_u32 s23, s38, s23
	s_and_b64 s[30:31], s[4:5], exec
	s_cselect_b32 s17, s23, s29
	s_cselect_b32 s19, s22, s28
	s_add_u32 s56, s1, 0x80
	s_addc_u32 s57, s0, 0
	s_add_u32 s58, s28, 0x100
	v_mov_b32_e32 v0, 0
	s_addc_u32 s59, s29, 0
	v_lshl_add_u64 v[140:141], s[26:27], 0, v[132:133]
	v_lshl_add_u64 v[142:143], s[26:27], 0, v[134:135]
	s_mov_b32 s60, -2
	s_mov_b64 s[28:29], 0
	v_mov_b64 v[0:1], 0
	v_mov_b64 v[2:3], 0
	v_mov_b64 v[4:5], 0
	v_mov_b64 v[6:7], 0
	v_mov_b64 v[8:9], 0
	v_mov_b64 v[10:11], 0
	v_mov_b64 v[16:17], 0
	v_mov_b64 v[18:19], 0
	v_mov_b64 v[24:25], 0
	v_mov_b64 v[26:27], 0
	v_mov_b64 v[32:33], 0
	v_mov_b64 v[34:35], 0
	v_mov_b64 v[40:41], 0
	v_mov_b64 v[42:43], 0
	v_mov_b64 v[48:49], 0
	v_mov_b64 v[50:51], 0
	v_mov_b64 v[12:13], 0
	v_mov_b64 v[14:15], 0
	v_mov_b64 v[20:21], 0
	v_mov_b64 v[22:23], 0
	v_mov_b64 v[28:29], 0
	v_mov_b64 v[30:31], 0
	v_mov_b64 v[36:37], 0
	v_mov_b64 v[38:39], 0
	v_mov_b64 v[44:45], 0
	v_mov_b64 v[46:47], 0
	v_mov_b64 v[52:53], 0
	v_mov_b64 v[54:55], 0
	v_mov_b64 v[56:57], 0
	v_mov_b64 v[58:59], 0
	v_mov_b64 v[60:61], 0
	v_mov_b64 v[62:63], 0
	v_mov_b64 v[64:65], 0
	v_mov_b64 v[66:67], 0
	v_mov_b64 v[68:69], 0
	v_mov_b64 v[70:71], 0
	v_mov_b64 v[76:77], 0
	v_mov_b64 v[78:79], 0
	v_mov_b64 v[84:85], 0
	v_mov_b64 v[86:87], 0
	v_mov_b64 v[88:89], 0
	v_mov_b64 v[90:91], 0
	v_mov_b64 v[96:97], 0
	v_mov_b64 v[98:99], 0
	v_mov_b64 v[104:105], 0
	v_mov_b64 v[106:107], 0
	v_mov_b64 v[112:113], 0
	v_mov_b64 v[114:115], 0
	v_mov_b64 v[72:73], 0
	v_mov_b64 v[74:75], 0
	v_mov_b64 v[80:81], 0
	v_mov_b64 v[82:83], 0
	v_mov_b64 v[92:93], 0
	v_mov_b64 v[94:95], 0
	v_mov_b64 v[100:101], 0
	v_mov_b64 v[102:103], 0
	v_mov_b64 v[108:109], 0
	v_mov_b64 v[110:111], 0
	v_mov_b64 v[116:117], 0
	v_mov_b64 v[118:119], 0
	v_mov_b64 v[120:121], 0
	v_mov_b64 v[122:123], 0
	v_mov_b64 v[124:125], 0
	v_mov_b64 v[126:127], 0

; template <class Epi, bool ALIGN_EPI = true>
; __device__ __forceinline__ void gemm_phase(LAS unsigned char* lds, const Gemm g, const StaticOrder& S, const Epi& E) {
;     ...
;         const bool has_next = S.next(ui + 1, nxt);
;         const char* nA = has_next ? (const char*)g.A + (size_t)nxt.pm * tstepA + (size_t)nxt.pn * g.a_pn_off * 2 : cA; const char* nB = has_next ? (const char*)g.Bt + (size_t)nxt.pn * tstepB : cB;
;     ...
;         for (int a = 0; a < 2; ++a)
; #pragma unroll
;             for (int b = 0; b < 2; ++b)
; #pragma unroll
;                 for (int m = 0; m < 4; ++m)
; #pragma unroll
;                     for (int n = 0; n < 2; ++n) acc[a][b][m][n] = (f32x4){0.f, 0.f, 0.f, 0.f};
.LBB0_151:
	s_lshl_b64 s[0:1], s[14:15], 17
	s_add_u32 s18, s8, s0
	s_addc_u32 s19, s9, s1
	s_and_b64 s[0:1], s[6:7], exec
	s_cselect_b32 s0, s19, s23
	s_cselect_b32 s1, s18, s22
	s_add_u32 s15, s4, 0x80
	v_mov_b32_e32 v0, 0
	s_addc_u32 s17, s5, 0
	s_mov_b32 s30, 0
	s_mov_b64 s[26:27], -1
	s_mov_b64 s[28:29], 0
	v_mov_b64 v[0:1], 0
	v_mov_b64 v[2:3], 0
	v_mov_b64 v[4:5], 0
	v_mov_b64 v[6:7], 0
	v_mov_b64 v[8:9], 0
	v_mov_b64 v[10:11], 0
	v_mov_b64 v[16:17], 0
	v_mov_b64 v[18:19], 0
	v_mov_b64 v[24:25], 0
	v_mov_b64 v[26:27], 0
	v_mov_b64 v[32:33], 0
	v_mov_b64 v[34:35], 0
	v_mov_b64 v[40:41], 0
	v_mov_b64 v[42:43], 0
	v_mov_b64 v[48:49], 0
	v_mov_b64 v[50:51], 0
	v_mov_b64 v[12:13], 0
	v_mov_b64 v[14:15], 0
	v_mov_b64 v[20:21], 0
	v_mov_b64 v[22:23], 0
	v_mov_b64 v[28:29], 0
	v_mov_b64 v[30:31], 0
	v_mov_b64 v[36:37], 0
	v_mov_b64 v[38:39], 0
	v_mov_b64 v[44:45], 0
	v_mov_b64 v[46:47], 0
	v_mov_b64 v[52:53], 0
	v_mov_b64 v[54:55], 0
	v_mov_b64 v[56:57], 0
	v_mov_b64 v[58:59], 0
	v_mov_b64 v[60:61], 0
	v_mov_b64 v[62:63], 0
	v_mov_b64 v[64:65], 0
	v_mov_b64 v[66:67], 0
	v_mov_b64 v[68:69], 0
	v_mov_b64 v[70:71], 0
	v_mov_b64 v[76:77], 0
	v_mov_b64 v[78:79], 0
	v_mov_b64 v[84:85], 0
	v_mov_b64 v[86:87], 0
	v_mov_b64 v[88:89], 0
	v_mov_b64 v[90:91], 0
	v_mov_b64 v[96:97], 0
	v_mov_b64 v[98:99], 0
	v_mov_b64 v[104:105], 0
	v_mov_b64 v[106:107], 0
	v_mov_b64 v[112:113], 0
	v_mov_b64 v[114:115], 0
	v_mov_b64 v[72:73], 0
	v_mov_b64 v[74:75], 0
	v_mov_b64 v[80:81], 0
	v_mov_b64 v[82:83], 0
	v_mov_b64 v[92:93], 0
	v_mov_b64 v[94:95], 0
	v_mov_b64 v[100:101], 0
	v_mov_b64 v[102:103], 0
	v_mov_b64 v[108:109], 0
	v_mov_b64 v[110:111], 0
	v_mov_b64 v[116:117], 0
	v_mov_b64 v[118:119], 0
	v_mov_b64 v[120:121], 0
	v_mov_b64 v[122:123], 0
	v_mov_b64 v[124:125], 0
	v_mov_b64 v[126:127], 0

; template <class Epi, bool ALIGN_EPI = true>
; __device__ __forceinline__ void gemm_phase(LAS unsigned char* lds, const Gemm g, const StaticOrder& S, const Epi& E) {
;     ...
;         const bool has_next = S.next(ui + 1, nxt);
;         const char* nA = has_next ? (const char*)g.A + (size_t)nxt.pm * tstepA + (size_t)nxt.pn * g.a_pn_off * 2 : cA; const char* nB = has_next ? (const char*)g.Bt + (size_t)nxt.pn * tstepB : cB;
;     ...
;         for (int a = 0; a < 2; ++a)
; #pragma unroll
;             for (int b = 0; b < 2; ++b)
; #pragma unroll
;                 for (int m = 0; m < 4; ++m)
; #pragma unroll
;                     for (int n = 0; n < 2; ++n) acc[a][b][m][n] = (f32x4){0.f, 0.f, 0.f, 0.f};
.LBB0_695:
	s_ashr_i32 s19, s18, 31
	s_lshl_b64 s[0:1], s[18:19], 21
	v_readlane_b32 s22, v255, 44
	v_readlane_b32 s23, v255, 45
	s_add_u32 s22, s22, s0
	s_addc_u32 s23, s23, s1
	s_and_b64 s[0:1], s[8:9], exec
	s_cselect_b32 s1, s22, s26
	s_cselect_b32 s0, s23, s27
	s_add_u32 s19, s1, 0x80
	s_addc_u32 s52, s0, 0
	s_add_u32 s53, s28, 0x100
	v_mov_b32_e32 v0, 0
	s_waitcnt vmcnt(0)
	v_lshl_add_u64 v[128:129], s[26:27], 0, v[150:151]
	v_lshl_add_u64 v[130:131], s[26:27], 0, v[152:153]
	s_addc_u32 s54, s29, 0
	s_mov_b32 s55, -2
	s_mov_b64 s[8:9], 0
	v_mov_b64 v[0:1], 0
	v_mov_b64 v[2:3], 0
	v_mov_b64 v[4:5], 0
	v_mov_b64 v[6:7], 0
	v_mov_b64 v[12:13], 0
	v_mov_b64 v[14:15], 0
	v_mov_b64 v[20:21], 0
	v_mov_b64 v[22:23], 0
	v_mov_b64 v[32:33], 0
	v_mov_b64 v[34:35], 0
	v_mov_b64 v[36:37], 0
	v_mov_b64 v[38:39], 0
	v_mov_b64 v[44:45], 0
	v_mov_b64 v[46:47], 0
	v_mov_b64 v[52:53], 0
	v_mov_b64 v[54:55], 0
	v_mov_b64 v[8:9], 0
	v_mov_b64 v[10:11], 0
	v_mov_b64 v[16:17], 0
	v_mov_b64 v[18:19], 0
	v_mov_b64 v[24:25], 0
	v_mov_b64 v[26:27], 0
	v_mov_b64 v[28:29], 0
	v_mov_b64 v[30:31], 0
	v_mov_b64 v[40:41], 0
	v_mov_b64 v[42:43], 0
	v_mov_b64 v[48:49], 0
	v_mov_b64 v[50:51], 0
	v_mov_b64 v[56:57], 0
	v_mov_b64 v[58:59], 0
	v_mov_b64 v[60:61], 0
	v_mov_b64 v[62:63], 0
	v_mov_b64 v[64:65], 0
	v_mov_b64 v[66:67], 0
	v_mov_b64 v[68:69], 0
	v_mov_b64 v[70:71], 0
	v_mov_b64 v[76:77], 0
	v_mov_b64 v[78:79], 0
	v_mov_b64 v[84:85], 0
	v_mov_b64 v[86:87], 0
	v_mov_b64 v[96:97], 0
	v_mov_b64 v[98:99], 0
	v_mov_b64 v[100:101], 0
	v_mov_b64 v[102:103], 0
	v_mov_b64 v[108:109], 0
	v_mov_b64 v[110:111], 0
	v_mov_b64 v[116:117], 0
	v_mov_b64 v[118:119], 0
	v_mov_b64 v[72:73], 0
	v_mov_b64 v[74:75], 0
	v_mov_b64 v[80:81], 0
	v_mov_b64 v[82:83], 0
	v_mov_b64 v[88:89], 0
	v_mov_b64 v[90:91], 0
	v_mov_b64 v[92:93], 0
	v_mov_b64 v[94:95], 0
	v_mov_b64 v[104:105], 0
	v_mov_b64 v[106:107], 0
	v_mov_b64 v[112:113], 0
	v_mov_b64 v[114:115], 0
	v_mov_b64 v[120:121], 0
	v_mov_b64 v[122:123], 0
	v_mov_b64 v[124:125], 0
	v_mov_b64 v[126:127], 0

; template <class Epi, bool ALIGN_EPI = true>
; __device__ __forceinline__ void gemm_phase(LAS unsigned char* lds, const Gemm g, const StaticOrder& S, const Epi& E) {
;     ...
;         const bool has_next = S.next(ui + 1, nxt);
;         const char* nA = has_next ? (const char*)g.A + (size_t)nxt.pm * tstepA + (size_t)nxt.pn * g.a_pn_off * 2 : cA; const char* nB = has_next ? (const char*)g.Bt + (size_t)nxt.pn * tstepB : cB;
;     ...
;         for (int a = 0; a < 2; ++a)
; #pragma unroll
;             for (int b = 0; b < 2; ++b)
; #pragma unroll
;                 for (int m = 0; m < 4; ++m)
; #pragma unroll
;                     for (int n = 0; n < 2; ++n) acc[a][b][m][n] = (f32x4){0.f, 0.f, 0.f, 0.f};
.LBB0_842:
	s_ashr_i32 s19, s18, 31
	s_lshl_b64 s[0:1], s[18:19], 20
	v_readlane_b32 s22, v255, 16
	v_readlane_b32 s23, v255, 17
	s_add_u32 s22, s22, s0
	s_addc_u32 s23, s23, s1
	s_and_b64 s[0:1], s[6:7], exec
	s_cselect_b32 s0, s23, s29
	s_cselect_b32 s1, s22, s28
	s_add_u32 s19, s20, 0x80
	s_addc_u32 s54, s21, 0
	s_add_u32 s55, s28, 0x100
	v_mov_b32_e32 v0, 0
	v_lshl_add_u64 v[136:137], s[26:27], 0, v[128:129]
	v_lshl_add_u64 v[138:139], s[26:27], 0, v[130:131]
	s_addc_u32 s56, s29, 0
	s_mov_b32 s57, -2
	s_mov_b64 s[6:7], 0
	v_mov_b64 v[0:1], 0
	v_mov_b64 v[2:3], 0
	v_mov_b64 v[4:5], 0
	v_mov_b64 v[6:7], 0
	v_mov_b64 v[16:17], 0
	v_mov_b64 v[18:19], 0
	v_mov_b64 v[20:21], 0
	v_mov_b64 v[22:23], 0
	v_mov_b64 v[32:33], 0
	v_mov_b64 v[34:35], 0
	v_mov_b64 v[36:37], 0
	v_mov_b64 v[38:39], 0
	v_mov_b64 v[48:49], 0
	v_mov_b64 v[50:51], 0
	v_mov_b64 v[52:53], 0
	v_mov_b64 v[54:55], 0
	v_mov_b64 v[8:9], 0
	v_mov_b64 v[10:11], 0
	v_mov_b64 v[12:13], 0
	v_mov_b64 v[14:15], 0
	v_mov_b64 v[24:25], 0
	v_mov_b64 v[26:27], 0
	v_mov_b64 v[28:29], 0
	v_mov_b64 v[30:31], 0
	v_mov_b64 v[40:41], 0
	v_mov_b64 v[42:43], 0
	v_mov_b64 v[44:45], 0
	v_mov_b64 v[46:47], 0
	v_mov_b64 v[56:57], 0
	v_mov_b64 v[58:59], 0
	v_mov_b64 v[60:61], 0
	v_mov_b64 v[62:63], 0
	v_mov_b64 v[64:65], 0
	v_mov_b64 v[66:67], 0
	v_mov_b64 v[68:69], 0
	v_mov_b64 v[70:71], 0
	v_mov_b64 v[80:81], 0
	v_mov_b64 v[82:83], 0
	v_mov_b64 v[84:85], 0
	v_mov_b64 v[86:87], 0
	v_mov_b64 v[96:97], 0
	v_mov_b64 v[98:99], 0
	v_mov_b64 v[100:101], 0
	v_mov_b64 v[102:103], 0
	v_mov_b64 v[112:113], 0
	v_mov_b64 v[114:115], 0
	v_mov_b64 v[116:117], 0
	v_mov_b64 v[118:119], 0
	v_mov_b64 v[72:73], 0
	v_mov_b64 v[74:75], 0
	v_mov_b64 v[76:77], 0
	v_mov_b64 v[78:79], 0
	v_mov_b64 v[88:89], 0
	v_mov_b64 v[90:91], 0
	v_mov_b64 v[92:93], 0
	v_mov_b64 v[94:95], 0
	v_mov_b64 v[104:105], 0
	v_mov_b64 v[106:107], 0
	v_mov_b64 v[108:109], 0
	v_mov_b64 v[110:111], 0
	v_mov_b64 v[120:121], 0
	v_mov_b64 v[122:123], 0
	v_mov_b64 v[124:125], 0
	v_mov_b64 v[126:127], 0

; template <class Epi, bool ALIGN_EPI = true>
; __device__ __forceinline__ void gemm_phase(LAS unsigned char* lds, const Gemm g, const StaticOrder& S, const Epi& E) {
;     ...
;         const bool has_next = S.next(ui + 1, nxt);
;         const char* nA = has_next ? (const char*)g.A + (size_t)nxt.pm * tstepA + (size_t)nxt.pn * g.a_pn_off * 2 : cA; const char* nB = has_next ? (const char*)g.Bt + (size_t)nxt.pn * tstepB : cB;
;     ...
;         for (int a = 0; a < 2; ++a)
; #pragma unroll
;             for (int b = 0; b < 2; ++b)
; #pragma unroll
;                 for (int m = 0; m < 4; ++m)
; #pragma unroll
;                     for (int n = 0; n < 2; ++n) acc[a][b][m][n] = (f32x4){0.f, 0.f, 0.f, 0.f};
.LBB0_987:
	s_ashr_i32 s21, s20, 31
	s_lshl_b64 s[24:25], s[20:21], 20
	v_readlane_b32 s30, v255, 18
	v_readlane_b32 s31, v255, 19
	s_add_u32 s24, s30, s24
	s_addc_u32 s25, s31, s25
	s_and_b64 s[4:5], s[4:5], exec
	s_cselect_b32 s21, s25, s29
	s_cselect_b32 s56, s24, s28
	s_add_u32 s57, s22, 0x80
	s_addc_u32 s58, s23, 0
	s_add_u32 s59, s28, 0x100
	v_mov_b32_e32 v0, 0
	v_lshl_add_u64 v[128:129], s[26:27], 0, v[144:145]
	v_lshl_add_u64 v[130:131], s[26:27], 0, v[146:147]
	s_addc_u32 s60, s29, 0
	s_mov_b32 s61, -2
	s_mov_b64 s[4:5], 0
	v_mov_b64 v[0:1], 0
	v_mov_b64 v[2:3], 0
	v_mov_b64 v[4:5], 0
	v_mov_b64 v[6:7], 0
	v_mov_b64 v[16:17], 0
	v_mov_b64 v[18:19], 0
	v_mov_b64 v[20:21], 0
	v_mov_b64 v[22:23], 0
	v_mov_b64 v[32:33], 0
	v_mov_b64 v[34:35], 0
	v_mov_b64 v[36:37], 0
	v_mov_b64 v[38:39], 0
	v_mov_b64 v[48:49], 0
	v_mov_b64 v[50:51], 0
	v_mov_b64 v[52:53], 0
	v_mov_b64 v[54:55], 0
	v_mov_b64 v[8:9], 0
	v_mov_b64 v[10:11], 0
	v_mov_b64 v[12:13], 0
	v_mov_b64 v[14:15], 0
	v_mov_b64 v[24:25], 0
	v_mov_b64 v[26:27], 0
	v_mov_b64 v[28:29], 0
	v_mov_b64 v[30:31], 0
	v_mov_b64 v[40:41], 0
	v_mov_b64 v[42:43], 0
	v_mov_b64 v[44:45], 0
	v_mov_b64 v[46:47], 0
	v_mov_b64 v[56:57], 0
	v_mov_b64 v[58:59], 0
	v_mov_b64 v[60:61], 0
	v_mov_b64 v[62:63], 0
	v_mov_b64 v[64:65], 0
	v_mov_b64 v[66:67], 0
	v_mov_b64 v[68:69], 0
	v_mov_b64 v[70:71], 0
	v_mov_b64 v[80:81], 0
	v_mov_b64 v[82:83], 0
	v_mov_b64 v[84:85], 0
	v_mov_b64 v[86:87], 0
	v_mov_b64 v[96:97], 0
	v_mov_b64 v[98:99], 0
	v_mov_b64 v[100:101], 0
	v_mov_b64 v[102:103], 0
	v_mov_b64 v[112:113], 0
	v_mov_b64 v[114:115], 0
	v_mov_b64 v[116:117], 0
	v_mov_b64 v[118:119], 0
	v_mov_b64 v[72:73], 0
	v_mov_b64 v[74:75], 0
	v_mov_b64 v[76:77], 0
	v_mov_b64 v[78:79], 0
	v_mov_b64 v[88:89], 0
	v_mov_b64 v[90:91], 0
	v_mov_b64 v[92:93], 0
	v_mov_b64 v[94:95], 0
	v_mov_b64 v[104:105], 0
	v_mov_b64 v[106:107], 0
	v_mov_b64 v[108:109], 0
	v_mov_b64 v[110:111], 0
	v_mov_b64 v[120:121], 0
	v_mov_b64 v[122:123], 0
	v_mov_b64 v[124:125], 0
	v_mov_b64 v[126:127], 0
